# attention epilogue: half-wave exchange (v_permlane32_swap) so the gated output goes out as dwordx4 stores and the gate values come in as dwordx4 loads instead of eight 8-byte pieces each
# baseline (speedup 1.0000x reference)
.Lat_rare7_ret:
	v_add_f32_e32 v128, v128, v134
	s_waitcnt vmcnt(0)
	s_barrier
	s_sub_u32 s82, s82, 1
	s_cmp_lg_u32 s82, 0
	s_cbranch_scc1 .Lat_loop
	s_setprio 0
	v_cvt_pk_bf16_f32 v112, v80, v81
	v_cvt_pk_bf16_f32 v113, v82, v83
	v_cvt_pk_bf16_f32 v114, v84, v85
	v_cvt_pk_bf16_f32 v115, v86, v87
	v_cvt_pk_bf16_f32 v116, v88, v89
	v_cvt_pk_bf16_f32 v117, v90, v91
	v_cvt_pk_bf16_f32 v118, v92, v93
	v_cvt_pk_bf16_f32 v119, v94, v95
	s_waitcnt lgkmcnt(0)
	v_mfma_f32_32x32x16_bf16 v[32:47], v[192:195], v[112:115], v[32:47]
	v_mfma_f32_32x32x16_bf16 v[48:63], v[196:199], v[112:115], v[48:63]
	v_mfma_f32_32x32x16_bf16 v[32:47], v[200:203], v[116:119], v[32:47]
	v_mfma_f32_32x32x16_bf16 v[48:63], v[240:243], v[116:119], v[48:63]
	s_nop 7
	s_nop 7
	s_waitcnt vmcnt(0)
	s_lshr_b32 s0, s2, 8
	s_lshl_b32 s0, s0, 13
	s_and_b32 s1, s2, 63
	s_lshl_b32 s1, s1, 7
	s_or_b32 s0, s0, s1
	s_bfe_u32 s1, s2, 0x20006
	s_lshl_b32 s1, s1, 7
	s_add_u32 s86, s94, 0x3200000
	s_addc_u32 s87, s95, 0
	s_add_u32 s88, s94, 0x1100200
	s_addc_u32 s89, s95, 0
	v_lshrrev_b32_e32 v0, 1, v138
	v_and_b32_e32 v0, 0xe0, v0
	v_and_or_b32 v0, v138, 31, v0
	v_add_u32_e32 v0, s0, v0
	v_bfe_u32 v3, v138, 5, 1
	v_lshl_add_u32 v3, v3, 3, s1
	v_mul_lo_u32 v1, v0, s64
	v_add_u32_e32 v1, v1, v3
	v_lshl_add_u32 v2, v0, 11, v3
	v_bfe_u32 v13, v138, 5, 1
	v_lshl_add_u32 v2, v13, 3, v2
	v_lshl_add_u32 v1, v13, 3, v1
	global_load_dwordx4 v[64:67], v1, s[86:87]
	global_load_dwordx4 v[68:71], v1, s[86:87] offset:32
	global_load_dwordx4 v[72:75], v1, s[86:87] offset:64
	global_load_dwordx4 v[76:79], v1, s[86:87] offset:96
	v_mbcnt_lo_u32_b32 v4, -1, 0
	v_mbcnt_hi_u32_b32 v4, -1, v4
	v_xor_b32_e32 v4, 32, v4
	v_lshlrev_b32_e32 v4, 2, v4
	ds_bpermute_b32 v5, v4, v128
	s_waitcnt lgkmcnt(0)
	v_add_f32_e32 v5, v128, v5
	v_mov_b32_e32 v7, 1.0
	v_div_scale_f32 v8, s[0:1], v5, v5, v7
	v_rcp_f32_e32 v9, v8
	s_nop 0
	v_fma_f32 v10, -v8, v9, 1.0
	v_fmac_f32_e32 v9, v10, v9
	v_div_scale_f32 v10, vcc, v7, v5, v7
	v_mul_f32_e32 v11, v10, v9
	v_fma_f32 v12, -v8, v11, v10
	v_fmac_f32_e32 v11, v12, v9
	v_fma_f32 v8, -v8, v11, v10
	v_div_fmas_f32 v8, v8, v9, v11
	v_div_fixup_f32 v6, v8, v5, v7
	s_waitcnt vmcnt(3)
	v_permlane32_swap_b32 v64, v66
	v_permlane32_swap_b32 v65, v67
	s_nop 0
	v_lshlrev_b32_e32 v16, 16, v64
	v_and_b32_e32 v17, 0xffff0000, v64
	v_lshlrev_b32_e32 v18, 16, v65
	v_and_b32_e32 v19, 0xffff0000, v65
	v_mul_f32_e32 v20, 0xbfb8aa3b, v16
	v_mul_f32_e32 v21, 0xbfb8aa3b, v17
	v_mul_f32_e32 v22, 0xbfb8aa3b, v18
	v_mul_f32_e32 v23, 0xbfb8aa3b, v19
	v_exp_f32_e32 v20, v20
	v_exp_f32_e32 v21, v21
	v_exp_f32_e32 v22, v22
	v_exp_f32_e32 v23, v23
	s_nop 0
	v_add_f32_e32 v20, 1.0, v20
	v_add_f32_e32 v21, 1.0, v21
	v_add_f32_e32 v22, 1.0, v22
	v_add_f32_e32 v23, 1.0, v23
	v_div_scale_f32 v8, s[0:1], v20, v20, v16
	v_rcp_f32_e32 v9, v8
	s_nop 0
	v_fma_f32 v10, -v8, v9, 1.0
	v_fmac_f32_e32 v9, v10, v9
	v_div_scale_f32 v10, vcc, v16, v20, v16
	v_mul_f32_e32 v11, v10, v9
	v_fma_f32 v12, -v8, v11, v10
	v_fmac_f32_e32 v11, v12, v9
	v_fma_f32 v8, -v8, v11, v10
	v_div_fmas_f32 v8, v8, v9, v11
	v_div_fixup_f32 v24, v8, v20, v16
	v_div_scale_f32 v8, s[0:1], v21, v21, v17
	v_rcp_f32_e32 v9, v8
	s_nop 0
	v_fma_f32 v10, -v8, v9, 1.0
	v_fmac_f32_e32 v9, v10, v9
	v_div_scale_f32 v10, vcc, v17, v21, v17
	v_mul_f32_e32 v11, v10, v9
	v_fma_f32 v12, -v8, v11, v10
	v_fmac_f32_e32 v11, v12, v9
	v_fma_f32 v8, -v8, v11, v10
	v_div_fmas_f32 v8, v8, v9, v11
	v_div_fixup_f32 v25, v8, v21, v17
	v_div_scale_f32 v8, s[0:1], v22, v22, v18
	v_rcp_f32_e32 v9, v8
	s_nop 0
	v_fma_f32 v10, -v8, v9, 1.0
	v_fmac_f32_e32 v9, v10, v9
	v_div_scale_f32 v10, vcc, v18, v22, v18
	v_mul_f32_e32 v11, v10, v9
	v_fma_f32 v12, -v8, v11, v10
	v_fmac_f32_e32 v11, v12, v9
	v_fma_f32 v8, -v8, v11, v10
	v_div_fmas_f32 v8, v8, v9, v11
	v_div_fixup_f32 v26, v8, v22, v18
	v_div_scale_f32 v8, s[0:1], v23, v23, v19
	v_rcp_f32_e32 v9, v8
	s_nop 0
	v_fma_f32 v10, -v8, v9, 1.0
	v_fmac_f32_e32 v9, v10, v9
	v_div_scale_f32 v10, vcc, v19, v23, v19
	v_mul_f32_e32 v11, v10, v9
	v_fma_f32 v12, -v8, v11, v10
	v_fmac_f32_e32 v11, v12, v9
	v_fma_f32 v8, -v8, v11, v10
	v_div_fmas_f32 v8, v8, v9, v11
	v_div_fixup_f32 v27, v8, v23, v19
	v_mul_f32_e32 v24, v24, v32
	v_mul_f32_e32 v25, v25, v33
	v_mul_f32_e32 v26, v26, v34
	v_mul_f32_e32 v27, v27, v35
	v_mul_f32_e32 v24, v24, v6
	v_mul_f32_e32 v25, v25, v6
	v_mul_f32_e32 v26, v26, v6
	v_mul_f32_e32 v27, v27, v6
	v_cvt_pk_bf16_f32 v28, v24, v25
	v_cvt_pk_bf16_f32 v29, v26, v27
	v_lshlrev_b32_e32 v16, 16, v66
	v_and_b32_e32 v17, 0xffff0000, v66
	v_lshlrev_b32_e32 v18, 16, v67
	v_and_b32_e32 v19, 0xffff0000, v67
	v_mul_f32_e32 v20, 0xbfb8aa3b, v16
	v_mul_f32_e32 v21, 0xbfb8aa3b, v17
	v_mul_f32_e32 v22, 0xbfb8aa3b, v18
	v_mul_f32_e32 v23, 0xbfb8aa3b, v19
	v_exp_f32_e32 v20, v20
	v_exp_f32_e32 v21, v21
	v_exp_f32_e32 v22, v22
	v_exp_f32_e32 v23, v23
	s_nop 0
	v_add_f32_e32 v20, 1.0, v20
	v_add_f32_e32 v21, 1.0, v21
	v_add_f32_e32 v22, 1.0, v22
	v_add_f32_e32 v23, 1.0, v23
	v_div_scale_f32 v8, s[0:1], v20, v20, v16
	v_rcp_f32_e32 v9, v8
	s_nop 0
	v_fma_f32 v10, -v8, v9, 1.0
	v_fmac_f32_e32 v9, v10, v9
	v_div_scale_f32 v10, vcc, v16, v20, v16
	v_mul_f32_e32 v11, v10, v9
	v_fma_f32 v12, -v8, v11, v10
	v_fmac_f32_e32 v11, v12, v9
	v_fma_f32 v8, -v8, v11, v10
	v_div_fmas_f32 v8, v8, v9, v11
	v_div_fixup_f32 v24, v8, v20, v16
	v_div_scale_f32 v8, s[0:1], v21, v21, v17
	v_rcp_f32_e32 v9, v8
	s_nop 0
	v_fma_f32 v10, -v8, v9, 1.0
	v_fmac_f32_e32 v9, v10, v9
	v_div_scale_f32 v10, vcc, v17, v21, v17
	v_mul_f32_e32 v11, v10, v9
	v_fma_f32 v12, -v8, v11, v10
	v_fmac_f32_e32 v11, v12, v9
	v_fma_f32 v8, -v8, v11, v10
	v_div_fmas_f32 v8, v8, v9, v11
	v_div_fixup_f32 v25, v8, v21, v17
	v_div_scale_f32 v8, s[0:1], v22, v22, v18
	v_rcp_f32_e32 v9, v8
	s_nop 0
	v_fma_f32 v10, -v8, v9, 1.0
	v_fmac_f32_e32 v9, v10, v9
	v_div_scale_f32 v10, vcc, v18, v22, v18
	v_mul_f32_e32 v11, v10, v9
	v_fma_f32 v12, -v8, v11, v10
	v_fmac_f32_e32 v11, v12, v9
	v_fma_f32 v8, -v8, v11, v10
	v_div_fmas_f32 v8, v8, v9, v11
	v_div_fixup_f32 v26, v8, v22, v18
	v_div_scale_f32 v8, s[0:1], v23, v23, v19
	v_rcp_f32_e32 v9, v8
	s_nop 0
	v_fma_f32 v10, -v8, v9, 1.0
	v_fmac_f32_e32 v9, v10, v9
	v_div_scale_f32 v10, vcc, v19, v23, v19
	v_mul_f32_e32 v11, v10, v9
	v_fma_f32 v12, -v8, v11, v10
	v_fmac_f32_e32 v11, v12, v9
	v_fma_f32 v8, -v8, v11, v10
	v_div_fmas_f32 v8, v8, v9, v11
	v_div_fixup_f32 v27, v8, v23, v19
	v_mul_f32_e32 v24, v24, v36
	v_mul_f32_e32 v25, v25, v37
	v_mul_f32_e32 v26, v26, v38
	v_mul_f32_e32 v27, v27, v39
	v_mul_f32_e32 v24, v24, v6
	v_mul_f32_e32 v25, v25, v6
	v_mul_f32_e32 v26, v26, v6
	v_mul_f32_e32 v27, v27, v6
	v_cvt_pk_bf16_f32 v30, v24, v25
	v_cvt_pk_bf16_f32 v31, v26, v27
	s_nop 1
	v_permlane32_swap_b32 v28, v30
	v_permlane32_swap_b32 v29, v31
	global_store_dwordx4 v2, v[28:31], s[88:89]
	s_waitcnt vmcnt(3)
	v_permlane32_swap_b32 v68, v70
	v_permlane32_swap_b32 v69, v71
	s_nop 0
	v_lshlrev_b32_e32 v16, 16, v68
	v_and_b32_e32 v17, 0xffff0000, v68
	v_lshlrev_b32_e32 v18, 16, v69
	v_and_b32_e32 v19, 0xffff0000, v69
	v_mul_f32_e32 v20, 0xbfb8aa3b, v16
	v_mul_f32_e32 v21, 0xbfb8aa3b, v17
	v_mul_f32_e32 v22, 0xbfb8aa3b, v18
	v_mul_f32_e32 v23, 0xbfb8aa3b, v19
	v_exp_f32_e32 v20, v20
	v_exp_f32_e32 v21, v21
	v_exp_f32_e32 v22, v22
	v_exp_f32_e32 v23, v23
	s_nop 0
	v_add_f32_e32 v20, 1.0, v20
	v_add_f32_e32 v21, 1.0, v21
	v_add_f32_e32 v22, 1.0, v22
	v_add_f32_e32 v23, 1.0, v23
	v_div_scale_f32 v8, s[0:1], v20, v20, v16
	v_rcp_f32_e32 v9, v8
	s_nop 0
	v_fma_f32 v10, -v8, v9, 1.0
	v_fmac_f32_e32 v9, v10, v9
	v_div_scale_f32 v10, vcc, v16, v20, v16
	v_mul_f32_e32 v11, v10, v9
	v_fma_f32 v12, -v8, v11, v10
	v_fmac_f32_e32 v11, v12, v9
	v_fma_f32 v8, -v8, v11, v10
	v_div_fmas_f32 v8, v8, v9, v11
	v_div_fixup_f32 v24, v8, v20, v16
	v_div_scale_f32 v8, s[0:1], v21, v21, v17
	v_rcp_f32_e32 v9, v8
	s_nop 0
	v_fma_f32 v10, -v8, v9, 1.0
	v_fmac_f32_e32 v9, v10, v9
	v_div_scale_f32 v10, vcc, v17, v21, v17
	v_mul_f32_e32 v11, v10, v9
	v_fma_f32 v12, -v8, v11, v10
	v_fmac_f32_e32 v11, v12, v9
	v_fma_f32 v8, -v8, v11, v10
	v_div_fmas_f32 v8, v8, v9, v11
	v_div_fixup_f32 v25, v8, v21, v17
	v_div_scale_f32 v8, s[0:1], v22, v22, v18
	v_rcp_f32_e32 v9, v8
	s_nop 0
	v_fma_f32 v10, -v8, v9, 1.0
	v_fmac_f32_e32 v9, v10, v9
	v_div_scale_f32 v10, vcc, v18, v22, v18
	v_mul_f32_e32 v11, v10, v9
	v_fma_f32 v12, -v8, v11, v10
	v_fmac_f32_e32 v11, v12, v9
	v_fma_f32 v8, -v8, v11, v10
	v_div_fmas_f32 v8, v8, v9, v11
	v_div_fixup_f32 v26, v8, v22, v18
	v_div_scale_f32 v8, s[0:1], v23, v23, v19
	v_rcp_f32_e32 v9, v8
	s_nop 0
	v_fma_f32 v10, -v8, v9, 1.0
	v_fmac_f32_e32 v9, v10, v9
	v_div_scale_f32 v10, vcc, v19, v23, v19
	v_mul_f32_e32 v11, v10, v9
	v_fma_f32 v12, -v8, v11, v10
	v_fmac_f32_e32 v11, v12, v9
	v_fma_f32 v8, -v8, v11, v10
	v_div_fmas_f32 v8, v8, v9, v11
	v_div_fixup_f32 v27, v8, v23, v19
	v_mul_f32_e32 v24, v24, v40
	v_mul_f32_e32 v25, v25, v41
	v_mul_f32_e32 v26, v26, v42
	v_mul_f32_e32 v27, v27, v43
	v_mul_f32_e32 v24, v24, v6
	v_mul_f32_e32 v25, v25, v6
	v_mul_f32_e32 v26, v26, v6
	v_mul_f32_e32 v27, v27, v6
	v_cvt_pk_bf16_f32 v28, v24, v25
	v_cvt_pk_bf16_f32 v29, v26, v27
	v_lshlrev_b32_e32 v16, 16, v70
	v_and_b32_e32 v17, 0xffff0000, v70
	v_lshlrev_b32_e32 v18, 16, v71
	v_and_b32_e32 v19, 0xffff0000, v71
	v_mul_f32_e32 v20, 0xbfb8aa3b, v16
	v_mul_f32_e32 v21, 0xbfb8aa3b, v17
	v_mul_f32_e32 v22, 0xbfb8aa3b, v18
	v_mul_f32_e32 v23, 0xbfb8aa3b, v19
	v_exp_f32_e32 v20, v20
	v_exp_f32_e32 v21, v21
	v_exp_f32_e32 v22, v22
	v_exp_f32_e32 v23, v23
	s_nop 0
	v_add_f32_e32 v20, 1.0, v20
	v_add_f32_e32 v21, 1.0, v21
	v_add_f32_e32 v22, 1.0, v22
	v_add_f32_e32 v23, 1.0, v23
	v_div_scale_f32 v8, s[0:1], v20, v20, v16
	v_rcp_f32_e32 v9, v8
	s_nop 0
	v_fma_f32 v10, -v8, v9, 1.0
	v_fmac_f32_e32 v9, v10, v9
	v_div_scale_f32 v10, vcc, v16, v20, v16
	v_mul_f32_e32 v11, v10, v9
	v_fma_f32 v12, -v8, v11, v10
	v_fmac_f32_e32 v11, v12, v9
	v_fma_f32 v8, -v8, v11, v10
	v_div_fmas_f32 v8, v8, v9, v11
	v_div_fixup_f32 v24, v8, v20, v16
	v_div_scale_f32 v8, s[0:1], v21, v21, v17
	v_rcp_f32_e32 v9, v8
	s_nop 0
	v_fma_f32 v10, -v8, v9, 1.0
	v_fmac_f32_e32 v9, v10, v9
	v_div_scale_f32 v10, vcc, v17, v21, v17
	v_mul_f32_e32 v11, v10, v9
	v_fma_f32 v12, -v8, v11, v10
	v_fmac_f32_e32 v11, v12, v9
	v_fma_f32 v8, -v8, v11, v10
	v_div_fmas_f32 v8, v8, v9, v11
	v_div_fixup_f32 v25, v8, v21, v17
	v_div_scale_f32 v8, s[0:1], v22, v22, v18
	v_rcp_f32_e32 v9, v8
	s_nop 0
	v_fma_f32 v10, -v8, v9, 1.0
	v_fmac_f32_e32 v9, v10, v9
	v_div_scale_f32 v10, vcc, v18, v22, v18
	v_mul_f32_e32 v11, v10, v9
	v_fma_f32 v12, -v8, v11, v10
	v_fmac_f32_e32 v11, v12, v9
	v_fma_f32 v8, -v8, v11, v10
	v_div_fmas_f32 v8, v8, v9, v11
	v_div_fixup_f32 v26, v8, v22, v18
	v_div_scale_f32 v8, s[0:1], v23, v23, v19
	v_rcp_f32_e32 v9, v8
	s_nop 0
	v_fma_f32 v10, -v8, v9, 1.0
	v_fmac_f32_e32 v9, v10, v9
	v_div_scale_f32 v10, vcc, v19, v23, v19
	v_mul_f32_e32 v11, v10, v9
	v_fma_f32 v12, -v8, v11, v10
	v_fmac_f32_e32 v11, v12, v9
	v_fma_f32 v8, -v8, v11, v10
	v_div_fmas_f32 v8, v8, v9, v11
	v_div_fixup_f32 v27, v8, v23, v19
	v_mul_f32_e32 v24, v24, v44
	v_mul_f32_e32 v25, v25, v45
	v_mul_f32_e32 v26, v26, v46
	v_mul_f32_e32 v27, v27, v47
	v_mul_f32_e32 v24, v24, v6
	v_mul_f32_e32 v25, v25, v6
	v_mul_f32_e32 v26, v26, v6
	v_mul_f32_e32 v27, v27, v6
	v_cvt_pk_bf16_f32 v30, v24, v25
	v_cvt_pk_bf16_f32 v31, v26, v27
	s_nop 1
	v_permlane32_swap_b32 v28, v30
	v_permlane32_swap_b32 v29, v31
	global_store_dwordx4 v2, v[28:31], s[88:89] offset:32
	s_waitcnt vmcnt(3)
	v_permlane32_swap_b32 v72, v74
	v_permlane32_swap_b32 v73, v75
	s_nop 0
	v_lshlrev_b32_e32 v16, 16, v72
	v_and_b32_e32 v17, 0xffff0000, v72
	v_lshlrev_b32_e32 v18, 16, v73
	v_and_b32_e32 v19, 0xffff0000, v73
	v_mul_f32_e32 v20, 0xbfb8aa3b, v16
	v_mul_f32_e32 v21, 0xbfb8aa3b, v17
	v_mul_f32_e32 v22, 0xbfb8aa3b, v18
	v_mul_f32_e32 v23, 0xbfb8aa3b, v19
	v_exp_f32_e32 v20, v20
	v_exp_f32_e32 v21, v21
	v_exp_f32_e32 v22, v22
	v_exp_f32_e32 v23, v23
	s_nop 0
	v_add_f32_e32 v20, 1.0, v20
	v_add_f32_e32 v21, 1.0, v21
	v_add_f32_e32 v22, 1.0, v22
	v_add_f32_e32 v23, 1.0, v23
	v_div_scale_f32 v8, s[0:1], v20, v20, v16
	v_rcp_f32_e32 v9, v8
	s_nop 0
	v_fma_f32 v10, -v8, v9, 1.0
	v_fmac_f32_e32 v9, v10, v9
	v_div_scale_f32 v10, vcc, v16, v20, v16
	v_mul_f32_e32 v11, v10, v9
	v_fma_f32 v12, -v8, v11, v10
	v_fmac_f32_e32 v11, v12, v9
	v_fma_f32 v8, -v8, v11, v10
	v_div_fmas_f32 v8, v8, v9, v11
	v_div_fixup_f32 v24, v8, v20, v16
	v_div_scale_f32 v8, s[0:1], v21, v21, v17
	v_rcp_f32_e32 v9, v8
	s_nop 0
	v_fma_f32 v10, -v8, v9, 1.0
	v_fmac_f32_e32 v9, v10, v9
	v_div_scale_f32 v10, vcc, v17, v21, v17
	v_mul_f32_e32 v11, v10, v9
	v_fma_f32 v12, -v8, v11, v10
	v_fmac_f32_e32 v11, v12, v9
	v_fma_f32 v8, -v8, v11, v10
	v_div_fmas_f32 v8, v8, v9, v11
	v_div_fixup_f32 v25, v8, v21, v17
	v_div_scale_f32 v8, s[0:1], v22, v22, v18
	v_rcp_f32_e32 v9, v8
	s_nop 0
	v_fma_f32 v10, -v8, v9, 1.0
	v_fmac_f32_e32 v9, v10, v9
	v_div_scale_f32 v10, vcc, v18, v22, v18
	v_mul_f32_e32 v11, v10, v9
	v_fma_f32 v12, -v8, v11, v10
	v_fmac_f32_e32 v11, v12, v9
	v_fma_f32 v8, -v8, v11, v10
	v_div_fmas_f32 v8, v8, v9, v11
	v_div_fixup_f32 v26, v8, v22, v18
	v_div_scale_f32 v8, s[0:1], v23, v23, v19
	v_rcp_f32_e32 v9, v8
	s_nop 0
	v_fma_f32 v10, -v8, v9, 1.0
	v_fmac_f32_e32 v9, v10, v9
	v_div_scale_f32 v10, vcc, v19, v23, v19
	v_mul_f32_e32 v11, v10, v9
	v_fma_f32 v12, -v8, v11, v10
	v_fmac_f32_e32 v11, v12, v9
	v_fma_f32 v8, -v8, v11, v10
	v_div_fmas_f32 v8, v8, v9, v11
	v_div_fixup_f32 v27, v8, v23, v19
	v_mul_f32_e32 v24, v24, v48
	v_mul_f32_e32 v25, v25, v49
	v_mul_f32_e32 v26, v26, v50
	v_mul_f32_e32 v27, v27, v51
	v_mul_f32_e32 v24, v24, v6
	v_mul_f32_e32 v25, v25, v6
	v_mul_f32_e32 v26, v26, v6
	v_mul_f32_e32 v27, v27, v6
	v_cvt_pk_bf16_f32 v28, v24, v25
	v_cvt_pk_bf16_f32 v29, v26, v27
	v_lshlrev_b32_e32 v16, 16, v74
	v_and_b32_e32 v17, 0xffff0000, v74
	v_lshlrev_b32_e32 v18, 16, v75
	v_and_b32_e32 v19, 0xffff0000, v75
	v_mul_f32_e32 v20, 0xbfb8aa3b, v16
	v_mul_f32_e32 v21, 0xbfb8aa3b, v17
	v_mul_f32_e32 v22, 0xbfb8aa3b, v18
	v_mul_f32_e32 v23, 0xbfb8aa3b, v19
	v_exp_f32_e32 v20, v20
	v_exp_f32_e32 v21, v21
	v_exp_f32_e32 v22, v22
	v_exp_f32_e32 v23, v23
	s_nop 0
	v_add_f32_e32 v20, 1.0, v20
	v_add_f32_e32 v21, 1.0, v21
	v_add_f32_e32 v22, 1.0, v22
	v_add_f32_e32 v23, 1.0, v23
	v_div_scale_f32 v8, s[0:1], v20, v20, v16
	v_rcp_f32_e32 v9, v8
	s_nop 0
	v_fma_f32 v10, -v8, v9, 1.0
	v_fmac_f32_e32 v9, v10, v9
	v_div_scale_f32 v10, vcc, v16, v20, v16
	v_mul_f32_e32 v11, v10, v9
	v_fma_f32 v12, -v8, v11, v10
	v_fmac_f32_e32 v11, v12, v9
	v_fma_f32 v8, -v8, v11, v10
	v_div_fmas_f32 v8, v8, v9, v11
	v_div_fixup_f32 v24, v8, v20, v16
	v_div_scale_f32 v8, s[0:1], v21, v21, v17
	v_rcp_f32_e32 v9, v8
	s_nop 0
	v_fma_f32 v10, -v8, v9, 1.0
	v_fmac_f32_e32 v9, v10, v9
	v_div_scale_f32 v10, vcc, v17, v21, v17
	v_mul_f32_e32 v11, v10, v9
	v_fma_f32 v12, -v8, v11, v10
	v_fmac_f32_e32 v11, v12, v9
	v_fma_f32 v8, -v8, v11, v10
	v_div_fmas_f32 v8, v8, v9, v11
	v_div_fixup_f32 v25, v8, v21, v17
	v_div_scale_f32 v8, s[0:1], v22, v22, v18
	v_rcp_f32_e32 v9, v8
	s_nop 0
	v_fma_f32 v10, -v8, v9, 1.0
	v_fmac_f32_e32 v9, v10, v9
	v_div_scale_f32 v10, vcc, v18, v22, v18
	v_mul_f32_e32 v11, v10, v9
	v_fma_f32 v12, -v8, v11, v10
	v_fmac_f32_e32 v11, v12, v9
	v_fma_f32 v8, -v8, v11, v10
	v_div_fmas_f32 v8, v8, v9, v11
	v_div_fixup_f32 v26, v8, v22, v18
	v_div_scale_f32 v8, s[0:1], v23, v23, v19
	v_rcp_f32_e32 v9, v8
	s_nop 0
	v_fma_f32 v10, -v8, v9, 1.0
	v_fmac_f32_e32 v9, v10, v9
	v_div_scale_f32 v10, vcc, v19, v23, v19
	v_mul_f32_e32 v11, v10, v9
	v_fma_f32 v12, -v8, v11, v10
	v_fmac_f32_e32 v11, v12, v9
	v_fma_f32 v8, -v8, v11, v10
	v_div_fmas_f32 v8, v8, v9, v11
	v_div_fixup_f32 v27, v8, v23, v19
	v_mul_f32_e32 v24, v24, v52
	v_mul_f32_e32 v25, v25, v53
	v_mul_f32_e32 v26, v26, v54
	v_mul_f32_e32 v27, v27, v55
	v_mul_f32_e32 v24, v24, v6
	v_mul_f32_e32 v25, v25, v6
	v_mul_f32_e32 v26, v26, v6
	v_mul_f32_e32 v27, v27, v6
	v_cvt_pk_bf16_f32 v30, v24, v25
	v_cvt_pk_bf16_f32 v31, v26, v27
	s_nop 1
	v_permlane32_swap_b32 v28, v30
	v_permlane32_swap_b32 v29, v31
	global_store_dwordx4 v2, v[28:31], s[88:89] offset:64
	s_waitcnt vmcnt(3)
	v_permlane32_swap_b32 v76, v78
	v_permlane32_swap_b32 v77, v79
	s_nop 0
	v_lshlrev_b32_e32 v16, 16, v76
	v_and_b32_e32 v17, 0xffff0000, v76
	v_lshlrev_b32_e32 v18, 16, v77
	v_and_b32_e32 v19, 0xffff0000, v77
	v_mul_f32_e32 v20, 0xbfb8aa3b, v16
	v_mul_f32_e32 v21, 0xbfb8aa3b, v17
	v_mul_f32_e32 v22, 0xbfb8aa3b, v18
	v_mul_f32_e32 v23, 0xbfb8aa3b, v19
	v_exp_f32_e32 v20, v20
	v_exp_f32_e32 v21, v21
	v_exp_f32_e32 v22, v22
	v_exp_f32_e32 v23, v23
	s_nop 0
	v_add_f32_e32 v20, 1.0, v20
	v_add_f32_e32 v21, 1.0, v21
	v_add_f32_e32 v22, 1.0, v22
	v_add_f32_e32 v23, 1.0, v23
	v_div_scale_f32 v8, s[0:1], v20, v20, v16
	v_rcp_f32_e32 v9, v8
	s_nop 0
	v_fma_f32 v10, -v8, v9, 1.0
	v_fmac_f32_e32 v9, v10, v9
	v_div_scale_f32 v10, vcc, v16, v20, v16
	v_mul_f32_e32 v11, v10, v9
	v_fma_f32 v12, -v8, v11, v10
	v_fmac_f32_e32 v11, v12, v9
	v_fma_f32 v8, -v8, v11, v10
	v_div_fmas_f32 v8, v8, v9, v11
	v_div_fixup_f32 v24, v8, v20, v16
	v_div_scale_f32 v8, s[0:1], v21, v21, v17
	v_rcp_f32_e32 v9, v8
	s_nop 0
	v_fma_f32 v10, -v8, v9, 1.0
	v_fmac_f32_e32 v9, v10, v9
	v_div_scale_f32 v10, vcc, v17, v21, v17
	v_mul_f32_e32 v11, v10, v9
	v_fma_f32 v12, -v8, v11, v10
	v_fmac_f32_e32 v11, v12, v9
	v_fma_f32 v8, -v8, v11, v10
	v_div_fmas_f32 v8, v8, v9, v11
	v_div_fixup_f32 v25, v8, v21, v17
	v_div_scale_f32 v8, s[0:1], v22, v22, v18
	v_rcp_f32_e32 v9, v8
	s_nop 0
	v_fma_f32 v10, -v8, v9, 1.0
	v_fmac_f32_e32 v9, v10, v9
	v_div_scale_f32 v10, vcc, v18, v22, v18
	v_mul_f32_e32 v11, v10, v9
	v_fma_f32 v12, -v8, v11, v10
	v_fmac_f32_e32 v11, v12, v9
	v_fma_f32 v8, -v8, v11, v10
	v_div_fmas_f32 v8, v8, v9, v11
	v_div_fixup_f32 v26, v8, v22, v18
	v_div_scale_f32 v8, s[0:1], v23, v23, v19
	v_rcp_f32_e32 v9, v8
	s_nop 0
	v_fma_f32 v10, -v8, v9, 1.0
	v_fmac_f32_e32 v9, v10, v9
	v_div_scale_f32 v10, vcc, v19, v23, v19
	v_mul_f32_e32 v11, v10, v9
	v_fma_f32 v12, -v8, v11, v10
	v_fmac_f32_e32 v11, v12, v9
	v_fma_f32 v8, -v8, v11, v10
	v_div_fmas_f32 v8, v8, v9, v11
	v_div_fixup_f32 v27, v8, v23, v19
	v_mul_f32_e32 v24, v24, v56
	v_mul_f32_e32 v25, v25, v57
	v_mul_f32_e32 v26, v26, v58
	v_mul_f32_e32 v27, v27, v59
	v_mul_f32_e32 v24, v24, v6
	v_mul_f32_e32 v25, v25, v6
	v_mul_f32_e32 v26, v26, v6
	v_mul_f32_e32 v27, v27, v6
	v_cvt_pk_bf16_f32 v28, v24, v25
	v_cvt_pk_bf16_f32 v29, v26, v27
	v_lshlrev_b32_e32 v16, 16, v78
	v_and_b32_e32 v17, 0xffff0000, v78
	v_lshlrev_b32_e32 v18, 16, v79
	v_and_b32_e32 v19, 0xffff0000, v79
	v_mul_f32_e32 v20, 0xbfb8aa3b, v16
	v_mul_f32_e32 v21, 0xbfb8aa3b, v17
	v_mul_f32_e32 v22, 0xbfb8aa3b, v18
	v_mul_f32_e32 v23, 0xbfb8aa3b, v19
	v_exp_f32_e32 v20, v20
	v_exp_f32_e32 v21, v21
	v_exp_f32_e32 v22, v22
	v_exp_f32_e32 v23, v23
	s_nop 0
	v_add_f32_e32 v20, 1.0, v20
	v_add_f32_e32 v21, 1.0, v21
	v_add_f32_e32 v22, 1.0, v22
	v_add_f32_e32 v23, 1.0, v23
	v_div_scale_f32 v8, s[0:1], v20, v20, v16
	v_rcp_f32_e32 v9, v8
	s_nop 0
	v_fma_f32 v10, -v8, v9, 1.0
	v_fmac_f32_e32 v9, v10, v9
	v_div_scale_f32 v10, vcc, v16, v20, v16
	v_mul_f32_e32 v11, v10, v9
	v_fma_f32 v12, -v8, v11, v10
	v_fmac_f32_e32 v11, v12, v9
	v_fma_f32 v8, -v8, v11, v10
	v_div_fmas_f32 v8, v8, v9, v11
	v_div_fixup_f32 v24, v8, v20, v16
	v_div_scale_f32 v8, s[0:1], v21, v21, v17
	v_rcp_f32_e32 v9, v8
	s_nop 0
	v_fma_f32 v10, -v8, v9, 1.0
	v_fmac_f32_e32 v9, v10, v9
	v_div_scale_f32 v10, vcc, v17, v21, v17
	v_mul_f32_e32 v11, v10, v9
	v_fma_f32 v12, -v8, v11, v10
	v_fmac_f32_e32 v11, v12, v9
	v_fma_f32 v8, -v8, v11, v10
	v_div_fmas_f32 v8, v8, v9, v11
	v_div_fixup_f32 v25, v8, v21, v17
	v_div_scale_f32 v8, s[0:1], v22, v22, v18
	v_rcp_f32_e32 v9, v8
	s_nop 0
	v_fma_f32 v10, -v8, v9, 1.0
	v_fmac_f32_e32 v9, v10, v9
	v_div_scale_f32 v10, vcc, v18, v22, v18
	v_mul_f32_e32 v11, v10, v9
	v_fma_f32 v12, -v8, v11, v10
	v_fmac_f32_e32 v11, v12, v9
	v_fma_f32 v8, -v8, v11, v10
	v_div_fmas_f32 v8, v8, v9, v11
	v_div_fixup_f32 v26, v8, v22, v18
	v_div_scale_f32 v8, s[0:1], v23, v23, v19
	v_rcp_f32_e32 v9, v8
	s_nop 0
	v_fma_f32 v10, -v8, v9, 1.0
	v_fmac_f32_e32 v9, v10, v9
	v_div_scale_f32 v10, vcc, v19, v23, v19
	v_mul_f32_e32 v11, v10, v9
	v_fma_f32 v12, -v8, v11, v10
	v_fmac_f32_e32 v11, v12, v9
	v_fma_f32 v8, -v8, v11, v10
	v_div_fmas_f32 v8, v8, v9, v11
	v_div_fixup_f32 v27, v8, v23, v19
	v_mul_f32_e32 v24, v24, v60
	v_mul_f32_e32 v25, v25, v61
	v_mul_f32_e32 v26, v26, v62
	v_mul_f32_e32 v27, v27, v63
	v_mul_f32_e32 v24, v24, v6
	v_mul_f32_e32 v25, v25, v6
	v_mul_f32_e32 v26, v26, v6
	v_mul_f32_e32 v27, v27, v6
	v_cvt_pk_bf16_f32 v30, v24, v25
	v_cvt_pk_bf16_f32 v31, v26, v27
	s_nop 1
	v_permlane32_swap_b32 v28, v30
	v_permlane32_swap_b32 v29, v31
	global_store_dwordx4 v2, v[28:31], s[88:89] offset:96
	s_add_i32 s2, s2, s71
	v_readlane_b32 s0, v206, 49
	s_nop 0
	s_cmp_ge_u32 s2, s0
	s_cbranch_scc0 .LBB0_350
	s_branch .LBB0_343
